# v86 plus s=2: workgroups with id bit 3 set run their small_gates wave units before their tiled-GEMM units (streaming overlaps MFMA work of the other half)
# baseline (speedup 1.0000x reference)
.LBB0_18:
	s_load_dwordx2 s[2:3], s[0:1], 0xf0
	s_add_u32 s4, s74, 0x4000000
	s_addc_u32 s5, s75, 0
	s_add_u32 s30, s74, 0x5000000
	s_addc_u32 s31, s75, 0
	s_waitcnt lgkmcnt(0)
	s_mul_i32 s2, s3, s2
	s_load_dword s3, s[0:1], 0xf8
	v_writelane_b32 v254, s4, 3
	s_cmp_eq_u64 s[74:75], 0
	v_mov_b32_e32 v1, 0
	v_writelane_b32 v254, s5, 4
	s_cselect_b64 s[4:5], -1, 0
	v_writelane_b32 v254, s4, 5
	s_waitcnt lgkmcnt(0)
	s_mul_i32 s26, s2, s3
	s_add_u32 s2, s22, 0x1000
	v_writelane_b32 v254, s5, 6
	s_addc_u32 s3, s23, 0
	v_writelane_b32 v254, s2, 7
	v_mbcnt_lo_u32_b32 v0, -1, 0
	s_mov_b32 s29, 0x40000
	v_writelane_b32 v254, s3, 8
	s_add_u32 s2, s22, 0x1100
	s_addc_u32 s3, s23, 0
	v_writelane_b32 v254, s2, 9
	v_mov_b32_e32 v172, 0x3ecc95a3
	v_mov_b32_e32 v173, 0x358637bd
	v_writelane_b32 v254, s3, 10
	s_add_u32 s2, s22, 0x1200
	s_addc_u32 s3, s23, 0
	v_writelane_b32 v254, s2, 11
	v_mov_b32_e32 v145, 0xc2400000
	v_mbcnt_hi_u32_b32 v174, -1, v0
	v_writelane_b32 v254, s3, 12
	s_add_u32 s2, s22, 0x1300
	s_addc_u32 s3, s23, 0
	v_writelane_b32 v254, s2, 13
	s_cmp_eq_u32 s10, 15
	v_mov_b32_e32 v175, 0x7f800000
	v_writelane_b32 v254, s3, 14
	s_cselect_b64 s[2:3], -1, 0
	v_writelane_b32 v254, s2, 15
	s_cmp_eq_u32 s10, 14
	v_mov_b32_e32 v176, 0x7fc00000
	v_writelane_b32 v254, s3, 16
	s_cselect_b64 s[2:3], -1, 0
	v_writelane_b32 v254, s2, 17
	s_cmp_eq_u32 s10, 13
	v_mov_b32_e32 v177, 0xff800000
	v_writelane_b32 v254, s3, 18
	s_cselect_b64 s[2:3], -1, 0
	v_writelane_b32 v254, s2, 19
	s_cmp_eq_u32 s10, 12
	v_mov_b32_e32 v178, 0x9fc
	v_writelane_b32 v254, s3, 20
	s_cselect_b64 s[2:3], -1, 0
	v_writelane_b32 v254, s2, 21
	s_cmp_eq_u32 s10, 11
	v_mov_b32_e32 v179, 0x41b17218
	v_writelane_b32 v254, s3, 22
	s_cselect_b64 s[2:3], -1, 0
	v_writelane_b32 v254, s2, 23
	s_cmp_eq_u32 s10, 10
	v_mov_b32_e32 v146, 0x3f317218
	v_writelane_b32 v254, s3, 24
	s_cselect_b64 s[2:3], -1, 0
	v_writelane_b32 v254, s2, 25
	s_cmp_eq_u32 s10, 9
	v_mov_b32_e32 v180, 1
	v_writelane_b32 v254, s3, 26
	s_cselect_b64 s[2:3], -1, 0
	v_writelane_b32 v254, s2, 27
	s_cmp_eq_u32 s10, 8
	v_mov_b32_e32 v220, v1
	v_writelane_b32 v254, s3, 28
	s_cselect_b64 s[2:3], -1, 0
	v_writelane_b32 v254, s2, 29
	s_cmp_eq_u32 s10, 7
	v_mov_b32_e32 v221, v1
	v_writelane_b32 v254, s3, 30
	s_cselect_b64 s[2:3], -1, 0
	v_writelane_b32 v254, s2, 31
	s_cmp_eq_u32 s10, 6
	v_mov_b32_e32 v222, v1
	v_writelane_b32 v254, s3, 32
	s_cselect_b64 s[2:3], -1, 0
	v_writelane_b32 v254, s2, 33
	s_cmp_eq_u32 s10, 5
	v_mov_b32_e32 v223, v1
	v_writelane_b32 v254, s3, 34
	s_cselect_b64 s[2:3], -1, 0
	v_writelane_b32 v254, s2, 35
	s_cmp_eq_u32 s10, 4
	v_mov_b32_e32 v181, 0
	v_writelane_b32 v254, s3, 36
	s_cselect_b64 s[2:3], -1, 0
	v_writelane_b32 v254, s2, 37
	s_cmp_eq_u32 s10, 3
	s_movk_i32 s18, 0x1e00
	v_writelane_b32 v254, s3, 38
	s_cselect_b64 s[2:3], -1, 0
	v_writelane_b32 v254, s2, 39
	s_cmp_eq_u32 s10, 2
	s_mov_b32 s19, 0xbfb8aa3b
	v_writelane_b32 v254, s3, 40
	s_cselect_b64 s[2:3], -1, 0
	v_writelane_b32 v254, s2, 41
	s_cmp_eq_u32 s10, 1
	s_mov_b32 s86, 0x3f2aaaab
	v_writelane_b32 v254, s3, 42
	s_cselect_b64 s[2:3], -1, 0
	v_writelane_b32 v254, s2, 43
	s_cmp_eq_u32 s10, 0
	s_mov_b32 s87, 0x3f317218
	v_writelane_b32 v254, s3, 44
	s_cselect_b64 s[2:3], -1, 0
	v_writelane_b32 v254, s2, 45
	s_mov_b32 s15, 0x7f800000
	s_mov_b32 s88, 0x33800000
	v_writelane_b32 v254, s3, 46
	s_lshl_b32 s2, s10, 8
	s_add_u32 s2, s22, s2
	s_addc_u32 s3, s23, 0
	s_add_u32 s2, s2, 0x1400
	s_addc_u32 s3, s3, 0
	v_writelane_b32 v254, s2, 47
	s_mov_b32 s96, 0x800000
	s_mov_b32 s97, 0x3f317217
	v_writelane_b32 v254, s3, 48
	s_add_u32 s2, s22, 0x3400
	s_addc_u32 s3, s23, 0
	v_writelane_b32 v254, s2, 49
	s_movk_i32 s89, 0x90
	s_mov_b32 s33, 0xffff0000
	v_writelane_b32 v254, s3, 50
	s_add_u32 s2, s22, 0x3500
	s_addc_u32 s3, s23, 0
	v_writelane_b32 v254, s2, 51
	s_mov_b32 s17, 0x5040100
	s_movk_i32 s14, 0x1600
	v_writelane_b32 v254, s3, 52
	s_add_i32 s2, 0, 0x8800
	v_writelane_b32 v254, s2, 53
	s_add_i32 s2, 0, 0x11000
	v_writelane_b32 v254, s2, 54
	s_add_i32 s2, 0, 0x19800
	v_writelane_b32 v254, s2, 55
	s_add_i32 s2, 0, 0x8400
	v_writelane_b32 v254, s2, 56
	s_add_i32 s2, 0, 0x10800
	v_writelane_b32 v254, s2, 57
	s_add_i32 s2, 0, 0x1a800
	v_writelane_b32 v254, s2, 58
	s_add_i32 s2, 0, 0x257c0
	v_writelane_b32 v254, s2, 59
	s_add_i32 s2, 0, 0x257c4
	v_writelane_b32 v254, s2, 60
	v_writelane_b32 v254, s26, 61
	v_writelane_b32 v254, s30, 62
	s_mov_b64 s[2:3], 0
	s_mov_b32 s81, 0
	s_mov_b64 s[8:9], 0xf000
	s_mov_b64 s[12:13], 0x80
	v_writelane_b32 v254, s31, 63
	s_nop 3
	v_writelane_b32 v255, s2, 42
	s_nop 3
	v_writelane_b32 v255, s2, 50
	s_branch .LBB0_22

.Lsw2_entry:
	v_readlane_b32 s2, v255, 4
	s_add_u32 s30, s2, 0x1080000
	v_readlane_b32 s2, v255, 5
	s_addc_u32 s31, s2, 0
	v_readlane_b32 s2, v255, 3
	s_mul_i32 s2, s2, 3
	s_ashr_i32 s3, s2, 31
	s_lshl_b64 s[2:3], s[2:3], 18
	v_readlane_b32 s4, v255, 6
	s_add_u32 s2, s4, s2
	v_readlane_b32 s4, v255, 7
	s_addc_u32 s3, s4, s3
	s_add_u32 s34, s2, 0x40000
	s_addc_u32 s35, s3, 0
	v_readlane_b32 s11, v255, 16
	v_mov_b32_e32 v12, v170
	s_cmpk_lt_i32 s11, 0x700
	s_nop 0
	v_readfirstlane_b32 s3, v12
	s_cbranch_scc0 .LBB0_145
	v_readlane_b32 s2, v255, 50
	s_nop 3
	s_cmp_lg_u32 s2, 0
	s_cbranch_scc1 .Lsw2_gemm
	v_readlane_b32 s2, v255, 16
	s_nop 3
	s_bitcmp1_b32 s2, 3
	s_cbranch_scc0 .Lsw2_gemm
	s_mov_b32 s2, 1
	s_nop 3
	v_writelane_b32 v255, s2, 50
	s_nop 1
	s_branch .LBB0_145
.Lsw2_gemm:
	v_lshlrev_b32_e32 v0, 4, v12
	v_add_u32_e32 v2, 0x2000, v0
	v_ashrrev_i32_e32 v3, 31, v2
	v_lshrrev_b32_e32 v3, 22, v3
	v_add_u32_e32 v3, v2, v3
	v_ashrrev_i32_e32 v10, 10, v3
	v_mul_i32_i24_e32 v3, 0x400, v10
	v_sub_u32_e32 v2, v2, v3
	v_lshrrev_b32_e32 v3, 4, v2
	v_bitop3_b32 v2, v3, v2, 32 bitop3:0x6c
	v_ashrrev_i32_e32 v3, 31, v2
	v_lshrrev_b32_e32 v3, 26, v3
	v_add_u32_e32 v3, v2, v3
	v_lshlrev_b32_e32 v4, 3, v10
	v_ashrrev_i32_e32 v13, 6, v3
	v_and_b32_e32 v4, -16, v4
	v_add_u32_e32 v4, v13, v4
	v_and_b32_e32 v5, 3, v13
	s_mov_b32 s2, 0x1fffe0
	v_lshrrev_b32_e32 v6, 2, v4
	v_lshlrev_b32_e32 v7, 1, v4
	v_and_b32_e32 v3, 0xc0, v3
	v_and_or_b32 v5, v4, s2, v5
	v_and_b32_e32 v6, 4, v6
	v_and_b32_e32 v7, 24, v7
	v_sub_u32_e32 v2, v2, v3
	v_or3_b32 v5, v5, v6, v7
	v_lshlrev_b32_e32 v6, 5, v10
	v_ashrrev_i16_sdwa v2, v180, sext(v2) dst_sel:DWORD dst_unused:UNUSED_PAD src0_sel:DWORD src1_sel:BYTE_0
	v_and_b32_e32 v6, 32, v6
	v_bfe_i32 v14, v2, 0, 16
	v_add_lshl_u32 v2, v6, v14, 1
	v_lshl_add_u32 v130, v5, 11, v2
	v_lshl_add_u32 v132, v4, 11, v2
	v_bfe_i32 v2, v12, 27, 1
	v_lshrrev_b32_e32 v2, 22, v2
	v_add_u32_e32 v2, v0, v2
	v_and_b32_e32 v2, 0xfffffc00, v2
	v_sub_u32_e32 v0, v0, v2
	v_lshrrev_b32_e32 v2, 4, v0
	v_ashrrev_i32_e32 v3, 31, v12
	v_bitop3_b32 v0, v2, v0, 32 bitop3:0x6c
	v_lshrrev_b32_e32 v3, 26, v3
	v_ashrrev_i32_e32 v2, 31, v0
	v_add_u32_e32 v3, v12, v3
	v_lshrrev_b32_e32 v2, 26, v2
	v_ashrrev_i32_e32 v16, 6, v3
	v_add_u32_e32 v2, v0, v2
	v_lshlrev_b32_e32 v3, 3, v16
	v_ashrrev_i32_e32 v15, 6, v2
	v_and_b32_e32 v3, -16, v3
	v_add_u32_e32 v3, v15, v3
	v_and_b32_e32 v4, 3, v15
	s_ashr_i32 s7, s11, 31
	v_and_or_b32 v4, v3, s2, v4
	s_lshr_b32 s2, s7, 29
	s_add_i32 s2, s11, s2
	s_ashr_i32 s38, s3, 8
	s_ashr_i32 s5, s3, 6
	s_ashr_i32 s10, s2, 3
	s_and_b32 s2, s2, -8
	s_lshl_b32 s6, s5, 10
	s_lshl_b32 s4, s38, 6
	s_sub_i32 s2, s11, s2
	s_cmp_lt_i32 s2, 0
	s_movk_i32 s11, 0xe1
	s_cselect_b32 s11, s11, 0xe0
	s_mul_i32 s2, s2, s11
	s_add_i32 s2, s2, s10
	s_mul_hi_i32 s10, s2, 0x92492493
	s_add_i32 s10, s10, s2
	s_lshr_b32 s11, s10, 31
	s_ashr_i32 s10, s10, 6
	s_add_i32 s10, s10, s11
	s_lshl_b32 s11, s10, 3
	s_mulk_i32 s10, 0x70
	s_sub_i32 s10, s2, s10
	s_bfe_i32 s2, s10, 0x80000
	s_bfe_u32 s2, s2, 0x3000c
	s_add_i32 s20, s10, s2
	s_bfe_i32 s2, s20, 0x80000
	s_and_b32 s20, s20, 0xf8
	v_lshrrev_b32_e32 v5, 2, v3
	v_lshlrev_b32_e32 v6, 1, v3
	v_and_b32_e32 v2, 0xc0, v2
	s_sub_i32 s10, s10, s20
	v_and_b32_e32 v5, 4, v5
	v_and_b32_e32 v6, 24, v6
	v_sub_u32_e32 v0, v0, v2
	s_sext_i32_i8 s10, s10
	v_or3_b32 v4, v4, v5, v6
	v_lshlrev_b32_e32 v5, 5, v16
	v_ashrrev_i16_sdwa v0, v180, sext(v0) dst_sel:DWORD dst_unused:UNUSED_PAD src0_sel:DWORD src1_sel:BYTE_0
	s_add_i32 s50, s11, s10
	v_and_b32_e32 v5, 32, v5
	v_bfe_i32 v17, v0, 0, 16
	s_sext_i32_i16 s2, s2
	s_lshl_b32 s10, s50, 8
	v_and_b32_e32 v11, 15, v12
	v_add_lshl_u32 v2, v5, v17, 1
	s_lshr_b32 s2, s2, 3
	s_add_i32 s10, s10, s4
	v_lshl_add_u32 v0, v4, 11, v2
	v_lshl_add_u32 v134, v3, 11, v2
	v_or_b32_e32 v2, s10, v11
	s_ashr_i32 s51, s50, 31
	s_bfe_i64 s[10:11], s[2:3], 0x100000
	s_lshl_b64 s[20:21], s[50:51], 19
	s_lshl_b64 s[10:11], s[10:11], 19
	s_add_u32 s52, s30, s10
	v_ashrrev_i32_e32 v3, 31, v2
	s_addc_u32 s53, s31, s11
	s_add_i32 s10, s6, 0
	v_lshl_add_u64 v[2:3], v[2:3], 3, s[34:35]
	s_add_i32 m0, s10, 0x10000
	s_waitcnt vmcnt(0)
	flat_load_dwordx2 v[158:159], v[2:3]
	flat_load_dwordx2 v[156:157], v[2:3] offset:128
	flat_load_dwordx2 v[154:155], v[2:3] offset:256
	flat_load_dwordx2 v[152:153], v[2:3] offset:384
	flat_load_dwordx2 v[150:151], v[2:3] offset:1024
	flat_load_dwordx2 v[148:149], v[2:3] offset:1152
	flat_load_dwordx2 v[142:143], v[2:3] offset:1280
	flat_load_dwordx2 v[140:141], v[2:3] offset:1408
	v_mov_b32_e32 v131, v1
	global_load_lds_dwordx4 v0, s[52:53]
	s_add_i32 m0, s10, 0x12000
	s_add_u32 s36, s52, 0x40000
	global_load_lds_dwordx4 v130, s[52:53]
	s_addc_u32 s37, s53, 0
	s_add_i32 m0, s10, 0x14000
	v_mov_b32_e32 v135, v1
	global_load_lds_dwordx4 v0, s[36:37]
	s_add_i32 m0, s10, 0x16000
	s_add_u32 s54, s24, s20
	s_addc_u32 s55, s25, s21
	s_add_i32 s11, s10, 0x2000
	global_load_lds_dwordx4 v130, s[36:37]
	s_mov_b32 m0, s10
	s_add_u32 s20, s54, 0x40000
	global_load_lds_dwordx4 v134, s[54:55]
	s_mov_b32 m0, s11
	s_addc_u32 s21, s55, 0
	s_add_i32 s36, s10, 0x4000
	global_load_lds_dwordx4 v132, s[54:55]
	s_mov_b32 m0, s36
	s_add_i32 s37, s10, 0x6000
	global_load_lds_dwordx4 v134, s[20:21]
	s_mov_b32 m0, s37
	v_mov_b32_e32 v133, v1
	global_load_lds_dwordx4 v132, s[20:21]
	s_cmp_eq_u32 s38, 1
	v_lshl_add_u64 v[8:9], s[52:53], 0, v[0:1]
	v_lshl_add_u64 v[6:7], s[52:53], 0, v[130:131]
	v_lshl_add_u64 v[2:3], s[54:55], 0, v[134:135]
	s_cselect_b64 s[20:21], -1, 0
	s_cmp_lg_u32 s38, 1
	v_lshl_add_u64 v[4:5], s[54:55], 0, v[132:133]
	s_cbranch_scc1 .LBB0_132
	s_barrier

.LBB0_145:
	v_readlane_b32 s2, v255, 50
	s_nop 3
	s_cmp_eq_u32 s2, 2
	s_cbranch_scc0 .Lsw2_gates
	s_mov_b32 s2, 0
	s_nop 3
	v_writelane_b32 v255, s2, 50
	s_nop 1
	s_branch .LBB0_152

.LBB0_152:
	v_readlane_b32 s2, v255, 50
	s_nop 3
	s_cmp_eq_u32 s2, 1
	s_cbranch_scc0 .Lsw2_done
	s_mov_b32 s2, 2
	s_nop 3
	v_writelane_b32 v255, s2, 50
	s_waitcnt vmcnt(0)
	s_branch .Lsw2_entry
